# FFN-in GEMM K-loop: load-segment head VALU/SALU (address adds, m0, counter) moved above the preceding barrier; uniform flag inversion done with one s_andn2
# baseline (speedup 1.0000x reference)
.LBB0_258:
	s_mov_b32 s24, s21
	s_mov_b32 s20, s25
	s_ashr_i32 s25, s21, 31
	s_xor_b64 s[60:61], s[26:27], -1
	s_lshl_b64 s[12:13], s[24:25], 20
	s_add_u32 s12, s18, s12
	s_addc_u32 s13, s19, s13
	s_cmp_gt_i32 s33, 0
	s_cselect_b32 s14, 0x80000, 0
	s_add_u32 s48, s12, s14
	s_addc_u32 s49, s13, 0
	s_and_b64 s[12:13], s[36:37], exec
	s_mov_b32 s71, s33
	s_cselect_b32 s25, s49, s59
	s_cselect_b32 s33, s48, s58
	s_ashr_i32 s21, s20, 31
	s_lshl_b64 s[12:13], s[20:21], 20
	s_add_u32 s54, s22, s12
	s_addc_u32 s55, s23, s13
	s_and_b64 s[12:13], s[36:37], exec
	s_cselect_b32 s21, s55, s51
	s_cselect_b32 s73, s54, s50
	s_cmp_gt_i32 s71, -1
	s_cselect_b64 s[56:57], -1, 0
	s_add_u32 s12, s58, 0x80
	v_cndmask_b32_e64 v2, 0, 1, s[56:57]
	v_cndmask_b32_e64 v8, 0, 1, s[26:27]
	s_addc_u32 s13, s59, 0
	v_cndmask_b32_e64 v2, v8, v2, s[36:37]
	v_lshl_add_u64 v[8:9], s[12:13], 0, v[214:215]
	v_and_b32_e32 v2, 1, v2
	v_lshl_add_u64 v[220:221], v[8:9], 0, v[218:219]
	v_lshl_add_u64 v[8:9], s[12:13], 0, v[216:217]
	v_mov_b32_e32 v10, v3
	v_mov_b32_e32 v11, v3
	v_cmp_eq_u32_e32 vcc, 1, v2
	v_lshl_add_u64 v[222:223], v[8:9], 0, v[218:219]
	s_add_u32 s26, s50, 0x100
	v_mov_b32_e32 v8, v3
	v_mov_b32_e32 v9, v3
	v_mov_b32_e32 v72, 0
	v_mov_b64_e32 v[14:15], v[10:11]
	v_mov_b64_e32 v[26:27], v[10:11]
	v_mov_b64_e32 v[30:31], v[10:11]
	v_mov_b64_e32 v[42:43], v[10:11]
	v_mov_b64_e32 v[46:47], v[10:11]
	v_mov_b64_e32 v[58:59], v[10:11]
	v_mov_b64_e32 v[62:63], v[10:11]
	v_mov_b64_e32 v[18:19], v[10:11]
	v_mov_b64_e32 v[22:23], v[10:11]
	v_mov_b64_e32 v[34:35], v[10:11]
	v_mov_b64_e32 v[38:39], v[10:11]
	v_mov_b64_e32 v[50:51], v[10:11]
	v_mov_b64_e32 v[54:55], v[10:11]
	v_mov_b64_e32 v[66:67], v[10:11]
	v_mov_b64_e32 v[70:71], v[10:11]
	v_cndmask_b32_e64 v2, v246, 0, vcc
	s_addc_u32 s27, s51, 0
	s_mov_b32 s74, -2
	s_mov_b64 s[62:63], 0
	v_mov_b64_e32 v[12:13], v[8:9]
	v_mov_b64_e32 v[24:25], v[8:9]
	v_mov_b64_e32 v[28:29], v[8:9]
	v_mov_b64_e32 v[40:41], v[8:9]
	v_mov_b64_e32 v[44:45], v[8:9]
	v_mov_b64_e32 v[56:57], v[8:9]
	v_mov_b64_e32 v[60:61], v[8:9]
	v_mov_b64_e32 v[16:17], v[8:9]
	v_mov_b64_e32 v[20:21], v[8:9]
	v_mov_b64_e32 v[32:33], v[8:9]
	v_mov_b64_e32 v[36:37], v[8:9]
	v_mov_b64_e32 v[48:49], v[8:9]
	v_mov_b64_e32 v[52:53], v[8:9]
	v_mov_b64_e32 v[64:65], v[8:9]
	v_mov_b64_e32 v[68:69], v[8:9]
	v_mov_b32_e32 v73, v72
	v_mov_b32_e32 v74, v72
	v_mov_b32_e32 v75, v72
	v_mov_b32_e32 v76, v72
	v_mov_b32_e32 v77, v72
	v_mov_b32_e32 v78, v72
	v_mov_b32_e32 v79, v72
	v_mov_b32_e32 v88, v72
	v_mov_b32_e32 v89, v72
	v_mov_b32_e32 v90, v72
	v_mov_b32_e32 v91, v72
	v_mov_b32_e32 v92, v72
	v_mov_b32_e32 v93, v72
	v_mov_b32_e32 v94, v72
	v_mov_b32_e32 v95, v72
	v_mov_b32_e32 v104, v72
	v_mov_b32_e32 v105, v72
	v_mov_b32_e32 v106, v72
	v_mov_b32_e32 v107, v72
	v_mov_b32_e32 v108, v72
	v_mov_b32_e32 v109, v72
	v_mov_b32_e32 v110, v72
	v_mov_b32_e32 v111, v72
	v_mov_b32_e32 v120, v72
	v_mov_b32_e32 v121, v72
	v_mov_b32_e32 v122, v72
	v_mov_b32_e32 v123, v72
	v_mov_b32_e32 v124, v72
	v_mov_b32_e32 v125, v72
	v_mov_b32_e32 v126, v72
	v_mov_b32_e32 v127, v72
	v_mov_b32_e32 v80, v72
	v_mov_b32_e32 v81, v72
	v_mov_b32_e32 v82, v72
	v_mov_b32_e32 v83, v72
	v_mov_b32_e32 v84, v72
	v_mov_b32_e32 v85, v72
	v_mov_b32_e32 v86, v72
	v_mov_b32_e32 v87, v72
	v_mov_b32_e32 v96, v72
	v_mov_b32_e32 v97, v72
	v_mov_b32_e32 v98, v72
	v_mov_b32_e32 v99, v72
	v_mov_b32_e32 v100, v72
	v_mov_b32_e32 v101, v72
	v_mov_b32_e32 v102, v72
	v_mov_b32_e32 v103, v72
	v_mov_b32_e32 v112, v72
	v_mov_b32_e32 v113, v72
	v_mov_b32_e32 v114, v72
	v_mov_b32_e32 v115, v72
	v_mov_b32_e32 v116, v72
	v_mov_b32_e32 v117, v72
	v_mov_b32_e32 v118, v72
	v_mov_b32_e32 v119, v72
	v_mov_b32_e32 v128, v72
	v_mov_b32_e32 v129, v72
	v_mov_b32_e32 v130, v72
	v_mov_b32_e32 v131, v72
	v_mov_b32_e32 v132, v72
	v_mov_b32_e32 v133, v72
	v_mov_b32_e32 v134, v72
	v_mov_b32_e32 v135, v72
	v_add_u32_e32 v168, 0x10000, v232
	v_add_u32_e32 v180, 0x14000, v232
	v_lshl_add_u64 v[224:225], v[222:223], 0, s[62:63]
	s_add_i32 m0, s35, 0xc000
	s_branch .LBB0_260
.LBB0_259:
	s_add_i32 s74, s74, 2
	s_add_u32 s62, s62, 0x100
	s_addc_u32 s63, s63, 0
	v_add_u32_e32 v168, 0x10000, v232
	v_add_u32_e32 v180, 0x14000, v232
	v_lshl_add_u64 v[224:225], v[222:223], 0, s[62:63]
	s_add_i32 m0, s35, 0xc000
	s_barrier
	s_cmp_gt_u32 s74, 29
	s_cbranch_scc1 .LBB0_268
.LBB0_260:
	s_waitcnt lgkmcnt(0)
	ds_read_b128 v[148:151], v207
	ds_read_b128 v[164:167], v207 offset:1024
	ds_read_b128 v[144:147], v207 offset:2048
	ds_read_b128 v[160:163], v207 offset:3072
	ds_read_b128 v[140:143], v207 offset:4096
	ds_read_b128 v[156:159], v207 offset:5120
	ds_read_b128 v[136:139], v207 offset:6144
	ds_read_b128 v[152:155], v207 offset:7168
	ds_read_b128 v[184:187], v168
	ds_read_b128 v[188:191], v168 offset:1024
	ds_read_b128 v[192:195], v168 offset:2048
	ds_read_b128 v[196:199], v168 offset:3072
	ds_read_b128 v[168:171], v180
	ds_read_b128 v[172:175], v180 offset:1024
	ds_read_b128 v[176:179], v180 offset:2048
	ds_read_b128 v[180:183], v180 offset:3072
	global_load_lds_dwordx4 v[224:225], off
	v_lshl_add_u64 v[224:225], v[220:221], 0, s[62:63]
	s_add_i32 m0, s35, 0xe000
	s_nop 0
	global_load_lds_dwordx4 v[224:225], off
	s_waitcnt vmcnt(8)
	s_waitcnt lgkmcnt(0)
	s_barrier
	s_waitcnt lgkmcnt(0)
	v_mfma_f32_16x16x32_bf16 v[132:135], v[184:187], v[148:151], v[132:135]
	v_mfma_f32_16x16x32_bf16 v[132:135], v[188:191], v[164:167], v[132:135]
	v_mfma_f32_16x16x32_bf16 v[128:131], v[192:195], v[148:151], v[128:131]
	v_mfma_f32_16x16x32_bf16 v[128:131], v[196:199], v[164:167], v[128:131]
	v_mfma_f32_16x16x32_bf16 v[124:127], v[168:171], v[148:151], v[124:127]
	v_mfma_f32_16x16x32_bf16 v[124:127], v[172:175], v[164:167], v[124:127]
	v_mfma_f32_16x16x32_bf16 v[120:123], v[176:179], v[148:151], v[120:123]
	v_mfma_f32_16x16x32_bf16 v[120:123], v[180:183], v[164:167], v[120:123]
	v_mfma_f32_16x16x32_bf16 v[116:119], v[184:187], v[144:147], v[116:119]
	v_mfma_f32_16x16x32_bf16 v[116:119], v[188:191], v[160:163], v[116:119]
	v_mfma_f32_16x16x32_bf16 v[112:115], v[192:195], v[144:147], v[112:115]
	v_mfma_f32_16x16x32_bf16 v[112:115], v[196:199], v[160:163], v[112:115]
	v_mfma_f32_16x16x32_bf16 v[108:111], v[168:171], v[144:147], v[108:111]
	v_mfma_f32_16x16x32_bf16 v[108:111], v[172:175], v[160:163], v[108:111]
	v_mfma_f32_16x16x32_bf16 v[104:107], v[176:179], v[144:147], v[104:107]
	v_mfma_f32_16x16x32_bf16 v[104:107], v[180:183], v[160:163], v[104:107]
	v_mfma_f32_16x16x32_bf16 v[100:103], v[184:187], v[140:143], v[100:103]
	v_mfma_f32_16x16x32_bf16 v[100:103], v[188:191], v[156:159], v[100:103]
	v_mfma_f32_16x16x32_bf16 v[96:99], v[192:195], v[140:143], v[96:99]
	v_mfma_f32_16x16x32_bf16 v[96:99], v[196:199], v[156:159], v[96:99]
	v_mfma_f32_16x16x32_bf16 v[92:95], v[168:171], v[140:143], v[92:95]
	v_mfma_f32_16x16x32_bf16 v[92:95], v[172:175], v[156:159], v[92:95]
	v_mfma_f32_16x16x32_bf16 v[88:91], v[176:179], v[140:143], v[88:91]
	v_mfma_f32_16x16x32_bf16 v[88:91], v[180:183], v[156:159], v[88:91]
	v_mfma_f32_16x16x32_bf16 v[84:87], v[184:187], v[136:139], v[84:87]
	v_mfma_f32_16x16x32_bf16 v[84:87], v[188:191], v[152:155], v[84:87]
	v_mfma_f32_16x16x32_bf16 v[80:83], v[192:195], v[136:139], v[80:83]
	v_mfma_f32_16x16x32_bf16 v[80:83], v[196:199], v[152:155], v[80:83]
	v_mfma_f32_16x16x32_bf16 v[76:79], v[168:171], v[136:139], v[76:79]
	v_mfma_f32_16x16x32_bf16 v[76:79], v[172:175], v[152:155], v[76:79]
	v_mfma_f32_16x16x32_bf16 v[72:75], v[176:179], v[136:139], v[72:75]
	v_mfma_f32_16x16x32_bf16 v[72:75], v[180:183], v[152:155], v[72:75]
	s_andn2_b64 s[50:51], exec, s[60:61]
	s_barrier
	s_andn2_b64 vcc, exec, s[60:61]
	s_cbranch_vccnz .LBB0_262
	ds_read_b128 v[148:151], v207 offset:16384
	ds_read_b128 v[164:167], v207 offset:17408
	ds_read_b128 v[144:147], v207 offset:18432
	ds_read_b128 v[160:163], v207 offset:19456
	ds_read_b128 v[140:143], v207 offset:20480
	ds_read_b128 v[156:159], v207 offset:21504
	ds_read_b128 v[136:139], v207 offset:22528
	ds_read_b128 v[152:155], v207 offset:23552

.LBB0_264:
	v_cndmask_b32_e64 v241, v219, 0, s[52:53]
	v_cndmask_b32_e64 v240, v218, v2, s[52:53]
	v_lshl_add_u64 v[240:241], s[14:15], 0, v[240:241]
	s_mov_b32 m0, s45
	v_add_u32_e32 v168, 0x18000, v232
	v_add_u32_e32 v180, 0x1c000, v232
	v_lshl_add_u64 v[242:243], v[240:241], 0, v[4:5]
	s_barrier
	s_waitcnt lgkmcnt(0)
	ds_read_b128 v[148:151], v207 offset:32768
	ds_read_b128 v[164:167], v207 offset:33792
	ds_read_b128 v[144:147], v207 offset:34816
	ds_read_b128 v[160:163], v207 offset:35840
	ds_read_b128 v[140:143], v207 offset:36864
	ds_read_b128 v[156:159], v207 offset:37888
	ds_read_b128 v[136:139], v207 offset:38912
	ds_read_b128 v[152:155], v207 offset:39936
	ds_read_b128 v[184:187], v168
	ds_read_b128 v[188:191], v168 offset:1024
	ds_read_b128 v[192:195], v168 offset:2048
	ds_read_b128 v[196:199], v168 offset:3072
	ds_read_b128 v[168:171], v180
	ds_read_b128 v[172:175], v180 offset:1024
	ds_read_b128 v[176:179], v180 offset:2048
	ds_read_b128 v[180:183], v180 offset:3072
	global_load_lds_dwordx4 v[242:243], off
	v_lshl_add_u64 v[240:241], v[240:241], 0, v[210:211]
	s_mov_b32 m0, s47
	s_nop 0
	global_load_lds_dwordx4 v[240:241], off
	s_waitcnt vmcnt(8)
	s_waitcnt lgkmcnt(0)
	s_barrier
	s_waitcnt lgkmcnt(0)
	v_mfma_f32_16x16x32_bf16 v[132:135], v[184:187], v[148:151], v[132:135]
	v_mfma_f32_16x16x32_bf16 v[132:135], v[188:191], v[164:167], v[132:135]
	v_mfma_f32_16x16x32_bf16 v[128:131], v[192:195], v[148:151], v[128:131]
	v_mfma_f32_16x16x32_bf16 v[128:131], v[196:199], v[164:167], v[128:131]
	v_mfma_f32_16x16x32_bf16 v[124:127], v[168:171], v[148:151], v[124:127]
	v_mfma_f32_16x16x32_bf16 v[124:127], v[172:175], v[164:167], v[124:127]
	v_mfma_f32_16x16x32_bf16 v[120:123], v[176:179], v[148:151], v[120:123]
	v_mfma_f32_16x16x32_bf16 v[120:123], v[180:183], v[164:167], v[120:123]
	v_mfma_f32_16x16x32_bf16 v[116:119], v[184:187], v[144:147], v[116:119]
	v_mfma_f32_16x16x32_bf16 v[116:119], v[188:191], v[160:163], v[116:119]
	v_mfma_f32_16x16x32_bf16 v[112:115], v[192:195], v[144:147], v[112:115]
	v_mfma_f32_16x16x32_bf16 v[112:115], v[196:199], v[160:163], v[112:115]
	v_mfma_f32_16x16x32_bf16 v[108:111], v[168:171], v[144:147], v[108:111]
	v_mfma_f32_16x16x32_bf16 v[108:111], v[172:175], v[160:163], v[108:111]
	v_mfma_f32_16x16x32_bf16 v[104:107], v[176:179], v[144:147], v[104:107]
	v_mfma_f32_16x16x32_bf16 v[104:107], v[180:183], v[160:163], v[104:107]
	v_mfma_f32_16x16x32_bf16 v[100:103], v[184:187], v[140:143], v[100:103]
	v_mfma_f32_16x16x32_bf16 v[100:103], v[188:191], v[156:159], v[100:103]
	v_mfma_f32_16x16x32_bf16 v[96:99], v[192:195], v[140:143], v[96:99]
	v_mfma_f32_16x16x32_bf16 v[96:99], v[196:199], v[156:159], v[96:99]
	v_mfma_f32_16x16x32_bf16 v[92:95], v[168:171], v[140:143], v[92:95]
	v_mfma_f32_16x16x32_bf16 v[92:95], v[172:175], v[156:159], v[92:95]
	v_mfma_f32_16x16x32_bf16 v[88:91], v[176:179], v[140:143], v[88:91]
	v_mfma_f32_16x16x32_bf16 v[88:91], v[180:183], v[156:159], v[88:91]
	v_mfma_f32_16x16x32_bf16 v[84:87], v[184:187], v[136:139], v[84:87]
	v_mfma_f32_16x16x32_bf16 v[84:87], v[188:191], v[152:155], v[84:87]
	v_mfma_f32_16x16x32_bf16 v[80:83], v[192:195], v[136:139], v[80:83]
	v_mfma_f32_16x16x32_bf16 v[80:83], v[196:199], v[152:155], v[80:83]
	v_mfma_f32_16x16x32_bf16 v[76:79], v[168:171], v[136:139], v[76:79]
	v_mfma_f32_16x16x32_bf16 v[76:79], v[172:175], v[152:155], v[76:79]
	v_mfma_f32_16x16x32_bf16 v[72:75], v[176:179], v[136:139], v[72:75]
	v_mfma_f32_16x16x32_bf16 v[72:75], v[180:183], v[152:155], v[72:75]
	s_barrier
	s_and_b64 vcc, exec, s[50:51]
	s_cbranch_vccnz .LBB0_266
	ds_read_b128 v[148:151], v207 offset:49152
	ds_read_b128 v[164:167], v207 offset:50176
	ds_read_b128 v[144:147], v207 offset:51200
	ds_read_b128 v[160:163], v207 offset:52224
	ds_read_b128 v[140:143], v207 offset:53248
	ds_read_b128 v[156:159], v207 offset:54272
	ds_read_b128 v[136:139], v207 offset:55296
	ds_read_b128 v[152:155], v207 offset:56320
